# final RMSNorm loop: four iterations' loads in flight per thread (de-serialised load-wait-store ladder)
# baseline (speedup 1.0000x reference)
; DI int ltid(int wv) { asm volatile("" : "+s"(wv)); int l = __builtin_amdgcn_mbcnt_hi(~0u, __builtin_amdgcn_mbcnt_lo(~0u, 0u)); asm volatile("" : "+v"(l)); return wv * 64 + l; }
; DI float bflo(unsigned u) { return __uint_as_float(u << 16); }
; DI float bfhi(unsigned u) { return __uint_as_float(u & 0xffff0000u); }
; DI float rs_from_ss(u64 ssq) { return rsqrtf((float)ssq * (1.f / (1048576.f * 1024.f)) + EPS); }
; DI void phase_final(int wv, const ArgP a) {
;     float* out = a.out(); const u64* rowss = (const u64*)(a.ws() + O_ROWSS) + 4 * S; const float* g = a.in(27); const bf16_t* XBr = (const bf16_t*)(a.ws() + O_XB) + 2 * 1024;
;     for (size_t e = (size_t)blockIdx.x * 512 + ltid(wv); e < (size_t)S * 128; e += (size_t)gridDim.x * 512) { const int t = (int)(e >> 7), c = (int)(e & 127) * 8;
;         const float rs = rs_from_ss(rowss[t]); const u32x4 hb = __builtin_nontemporal_load((const u32x4*)(XBr + (size_t)t * 1024 + c)); const f32x4 g0 = *(const f32x4*)(g + c), g1 = *(const f32x4*)(g + c + 4);
;         const f32x4 v0 = (f32x4){bflo(hb.x), bfhi(hb.x), bflo(hb.y), bfhi(hb.y)} * rs * g0, v1 = (f32x4){bflo(hb.z), bfhi(hb.z), bflo(hb.w), bfhi(hb.w)} * rs * g1;
;         __builtin_nontemporal_store(v0, (f32x4*)(out + (size_t)t * 1024 + c)); __builtin_nontemporal_store(v1, (f32x4*)(out + (size_t)t * 1024 + c + 4)); }
; }
.LBB0_1992:
	v_and_b32_e32 v7, 0x3f8, v2
	v_lshlrev_b32_e32 v60, 1, v7
	v_lshlrev_b32_e32 v61, 2, v7
	v_mov_b32_e32 v62, 0
	v_mov_b32_e32 v63, 0
	global_load_dwordx4 v[12:15], v61, s[4:5]
	global_load_dwordx4 v[16:19], v61, s[4:5] offset:16
	s_mov_b64 s[30:31], 0x200000
.Lfin_loop:
	v_mov_b32_e32 v30, v0
	v_mov_b32_e32 v31, v1
	v_lshl_add_u64 v[32:33], v[30:31], 0, s[8:9]
	v_lshl_add_u64 v[34:35], v[32:33], 0, s[8:9]
	v_lshl_add_u64 v[36:37], v[34:35], 0, s[8:9]
	v_cmp_gt_u64_e64 s[20:21], s[30:31], v[30:31]
	v_lshrrev_b64 v[40:41], 7, v[30:31]
	v_cmp_gt_u64_e64 s[22:23], s[30:31], v[32:33]
	v_lshrrev_b64 v[42:43], 7, v[32:33]
	v_cmp_gt_u64_e64 s[24:25], s[30:31], v[34:35]
	v_lshrrev_b64 v[44:45], 7, v[34:35]
	v_cmp_gt_u64_e64 s[26:27], s[30:31], v[36:37]
	v_lshrrev_b64 v[46:47], 7, v[36:37]
	v_lshl_add_u64 v[100:101], v[40:41], 3, s[0:1]
	global_load_dwordx2 v[64:65], v[100:101], off
	v_lshlrev_b64 v[100:101], 11, v[40:41]
	v_lshl_add_u64 v[100:101], s[2:3], 0, v[100:101]
	v_add_co_u32_e32 v100, vcc, v100, v60
	s_nop 1
	v_addc_co_u32_e32 v101, vcc, 0, v101, vcc
	global_load_dwordx4 v[72:75], v[100:101], off nt
	v_lshlrev_b64 v[90:91], 12, v[40:41]
	v_lshl_add_u64 v[90:91], s[6:7], 0, v[90:91]
	v_add_co_u32_e32 v90, vcc, v90, v61
	s_nop 1
	v_addc_co_u32_e32 v91, vcc, 0, v91, vcc
	v_lshl_add_u64 v[100:101], v[42:43], 3, s[0:1]
	global_load_dwordx2 v[66:67], v[100:101], off
	v_lshlrev_b64 v[100:101], 11, v[42:43]
	v_lshl_add_u64 v[100:101], s[2:3], 0, v[100:101]
	v_add_co_u32_e32 v100, vcc, v100, v60
	s_nop 1
	v_addc_co_u32_e32 v101, vcc, 0, v101, vcc
	global_load_dwordx4 v[76:79], v[100:101], off nt
	v_lshlrev_b64 v[92:93], 12, v[42:43]
	v_lshl_add_u64 v[92:93], s[6:7], 0, v[92:93]
	v_add_co_u32_e32 v92, vcc, v92, v61
	s_nop 1
	v_addc_co_u32_e32 v93, vcc, 0, v93, vcc
	v_lshl_add_u64 v[100:101], v[44:45], 3, s[0:1]
	global_load_dwordx2 v[68:69], v[100:101], off
	v_lshlrev_b64 v[100:101], 11, v[44:45]
	v_lshl_add_u64 v[100:101], s[2:3], 0, v[100:101]
	v_add_co_u32_e32 v100, vcc, v100, v60
	s_nop 1
	v_addc_co_u32_e32 v101, vcc, 0, v101, vcc
	global_load_dwordx4 v[80:83], v[100:101], off nt
	v_lshlrev_b64 v[94:95], 12, v[44:45]
	v_lshl_add_u64 v[94:95], s[6:7], 0, v[94:95]
	v_add_co_u32_e32 v94, vcc, v94, v61
	s_nop 1
	v_addc_co_u32_e32 v95, vcc, 0, v95, vcc
	v_lshl_add_u64 v[100:101], v[46:47], 3, s[0:1]
	global_load_dwordx2 v[70:71], v[100:101], off
	v_lshlrev_b64 v[100:101], 11, v[46:47]
	v_lshl_add_u64 v[100:101], s[2:3], 0, v[100:101]
	v_add_co_u32_e32 v100, vcc, v100, v60
	s_nop 1
	v_addc_co_u32_e32 v101, vcc, 0, v101, vcc
	global_load_dwordx4 v[84:87], v[100:101], off nt
	v_lshlrev_b64 v[96:97], 12, v[46:47]
	v_lshl_add_u64 v[96:97], s[6:7], 0, v[96:97]
	v_add_co_u32_e32 v96, vcc, v96, v61
	s_nop 1
	v_addc_co_u32_e32 v97, vcc, 0, v97, vcc
	v_lshl_add_u64 v[0:1], v[36:37], 0, s[8:9]
	v_cmp_lt_u64_e32 vcc, s[14:15], v[0:1]
	s_or_b64 s[12:13], vcc, s[12:13]
	s_waitcnt vmcnt(6)
	v_ffbh_u32_e32 v4, v65
	v_min_u32_e32 v4, 32, v4
	v_lshlrev_b64 v[64:65], v4, v[64:65]
	v_min_u32_e32 v7, 1, v64
	v_or_b32_e32 v7, v65, v7
	v_cvt_f32_u32_e32 v7, v7
	v_sub_u32_e32 v4, 32, v4
	v_ldexp_f32 v4, v7, v4
	v_fmamk_f32 v4, v4, 0x30800000, v6
	v_mul_f32_e32 v7, 0x4b800000, v4
	v_cmp_gt_f32_e32 vcc, s16, v4
	s_nop 1
	v_cndmask_b32_e32 v4, v4, v7, vcc
	v_rsq_f32_e32 v4, v4
	s_nop 0
	v_mul_f32_e32 v7, 0x45800000, v4
	v_cndmask_b32_e32 v4, v4, v7, vcc
	v_lshlrev_b32_e32 v104, 16, v72
	v_and_b32_e32 v105, 0xffff0000, v72
	v_lshlrev_b32_e32 v106, 16, v73
	v_and_b32_e32 v107, 0xffff0000, v73
	v_lshlrev_b32_e32 v108, 16, v74
	v_and_b32_e32 v109, 0xffff0000, v74
	v_lshlrev_b32_e32 v110, 16, v75
	v_and_b32_e32 v111, 0xffff0000, v75
	v_pk_mul_f32 v[104:105], v[4:5], v[104:105] op_sel_hi:[0,1]
	v_pk_mul_f32 v[106:107], v[4:5], v[106:107] op_sel_hi:[0,1]
	v_pk_mul_f32 v[108:109], v[4:5], v[108:109] op_sel_hi:[0,1]
	v_pk_mul_f32 v[110:111], v[4:5], v[110:111] op_sel_hi:[0,1]
	v_pk_mul_f32 v[104:105], v[12:13], v[104:105]
	v_pk_mul_f32 v[106:107], v[14:15], v[106:107]
	v_pk_mul_f32 v[108:109], v[16:17], v[108:109]
	v_pk_mul_f32 v[110:111], v[18:19], v[110:111]
	s_waitcnt vmcnt(4)
; DI int ltid(int wv) { asm volatile("" : "+s"(wv)); int l = __builtin_amdgcn_mbcnt_hi(~0u, __builtin_amdgcn_mbcnt_lo(~0u, 0u)); asm volatile("" : "+v"(l)); return wv * 64 + l; }
; DI float bflo(unsigned u) { return __uint_as_float(u << 16); }
; DI float bfhi(unsigned u) { return __uint_as_float(u & 0xffff0000u); }
; DI float rs_from_ss(u64 ssq) { return rsqrtf((float)ssq * (1.f / (1048576.f * 1024.f)) + EPS); }
; DI void phase_final(int wv, const ArgP a) {
;     float* out = a.out(); const u64* rowss = (const u64*)(a.ws() + O_ROWSS) + 4 * S; const float* g = a.in(27); const bf16_t* XBr = (const bf16_t*)(a.ws() + O_XB) + 2 * 1024;
;     for (size_t e = (size_t)blockIdx.x * 512 + ltid(wv); e < (size_t)S * 128; e += (size_t)gridDim.x * 512) { const int t = (int)(e >> 7), c = (int)(e & 127) * 8;
;         const float rs = rs_from_ss(rowss[t]); const u32x4 hb = __builtin_nontemporal_load((const u32x4*)(XBr + (size_t)t * 1024 + c)); const f32x4 g0 = *(const f32x4*)(g + c), g1 = *(const f32x4*)(g + c + 4);
;         const f32x4 v0 = (f32x4){bflo(hb.x), bfhi(hb.x), bflo(hb.y), bfhi(hb.y)} * rs * g0, v1 = (f32x4){bflo(hb.z), bfhi(hb.z), bflo(hb.w), bfhi(hb.w)} * rs * g1;
;         __builtin_nontemporal_store(v0, (f32x4*)(out + (size_t)t * 1024 + c)); __builtin_nontemporal_store(v1, (f32x4*)(out + (size_t)t * 1024 + c + 4)); }
; }
	v_ffbh_u32_e32 v4, v67
	v_min_u32_e32 v4, 32, v4
	v_lshlrev_b64 v[66:67], v4, v[66:67]
	v_min_u32_e32 v7, 1, v66
	v_or_b32_e32 v7, v67, v7
	v_cvt_f32_u32_e32 v7, v7
	v_sub_u32_e32 v4, 32, v4
	v_ldexp_f32 v4, v7, v4
	v_fmamk_f32 v4, v4, 0x30800000, v6
	v_mul_f32_e32 v7, 0x4b800000, v4
	v_cmp_gt_f32_e32 vcc, s16, v4
	s_nop 1
	v_cndmask_b32_e32 v4, v4, v7, vcc
	v_rsq_f32_e32 v4, v4
	s_nop 0
	v_mul_f32_e32 v7, 0x45800000, v4
	v_cndmask_b32_e32 v4, v4, v7, vcc
	v_lshlrev_b32_e32 v112, 16, v76
	v_and_b32_e32 v113, 0xffff0000, v76
	v_lshlrev_b32_e32 v114, 16, v77
	v_and_b32_e32 v115, 0xffff0000, v77
	v_lshlrev_b32_e32 v116, 16, v78
	v_and_b32_e32 v117, 0xffff0000, v78
	v_lshlrev_b32_e32 v118, 16, v79
	v_and_b32_e32 v119, 0xffff0000, v79
	v_pk_mul_f32 v[112:113], v[4:5], v[112:113] op_sel_hi:[0,1]
	v_pk_mul_f32 v[114:115], v[4:5], v[114:115] op_sel_hi:[0,1]
	v_pk_mul_f32 v[116:117], v[4:5], v[116:117] op_sel_hi:[0,1]
	v_pk_mul_f32 v[118:119], v[4:5], v[118:119] op_sel_hi:[0,1]
	v_pk_mul_f32 v[112:113], v[12:13], v[112:113]
	v_pk_mul_f32 v[114:115], v[14:15], v[114:115]
	v_pk_mul_f32 v[116:117], v[16:17], v[116:117]
	v_pk_mul_f32 v[118:119], v[18:19], v[118:119]
	s_waitcnt vmcnt(2)
	v_ffbh_u32_e32 v4, v69
	v_min_u32_e32 v4, 32, v4
	v_lshlrev_b64 v[68:69], v4, v[68:69]
	v_min_u32_e32 v7, 1, v68
	v_or_b32_e32 v7, v69, v7
	v_cvt_f32_u32_e32 v7, v7
	v_sub_u32_e32 v4, 32, v4
	v_ldexp_f32 v4, v7, v4
	v_fmamk_f32 v4, v4, 0x30800000, v6
	v_mul_f32_e32 v7, 0x4b800000, v4
	v_cmp_gt_f32_e32 vcc, s16, v4
	s_nop 1
	v_cndmask_b32_e32 v4, v4, v7, vcc
	v_rsq_f32_e32 v4, v4
	s_nop 0
	v_mul_f32_e32 v7, 0x45800000, v4
	v_cndmask_b32_e32 v4, v4, v7, vcc
	v_lshlrev_b32_e32 v120, 16, v80
	v_and_b32_e32 v121, 0xffff0000, v80
	v_lshlrev_b32_e32 v122, 16, v81
	v_and_b32_e32 v123, 0xffff0000, v81
	v_lshlrev_b32_e32 v124, 16, v82
	v_and_b32_e32 v125, 0xffff0000, v82
	v_lshlrev_b32_e32 v126, 16, v83
	v_and_b32_e32 v127, 0xffff0000, v83
	v_pk_mul_f32 v[120:121], v[4:5], v[120:121] op_sel_hi:[0,1]
	v_pk_mul_f32 v[122:123], v[4:5], v[122:123] op_sel_hi:[0,1]
	v_pk_mul_f32 v[124:125], v[4:5], v[124:125] op_sel_hi:[0,1]
	v_pk_mul_f32 v[126:127], v[4:5], v[126:127] op_sel_hi:[0,1]
	v_pk_mul_f32 v[120:121], v[12:13], v[120:121]
	v_pk_mul_f32 v[122:123], v[14:15], v[122:123]
	v_pk_mul_f32 v[124:125], v[16:17], v[124:125]
	v_pk_mul_f32 v[126:127], v[18:19], v[126:127]
	s_waitcnt vmcnt(0)
	v_ffbh_u32_e32 v4, v71
	v_min_u32_e32 v4, 32, v4
	v_lshlrev_b64 v[70:71], v4, v[70:71]
	v_min_u32_e32 v7, 1, v70
	v_or_b32_e32 v7, v71, v7
	v_cvt_f32_u32_e32 v7, v7
	v_sub_u32_e32 v4, 32, v4
	v_ldexp_f32 v4, v7, v4
	v_fmamk_f32 v4, v4, 0x30800000, v6
	v_mul_f32_e32 v7, 0x4b800000, v4
	v_cmp_gt_f32_e32 vcc, s16, v4
	s_nop 1
	v_cndmask_b32_e32 v4, v4, v7, vcc
	v_rsq_f32_e32 v4, v4
	s_nop 0
	v_mul_f32_e32 v7, 0x45800000, v4
	v_cndmask_b32_e32 v4, v4, v7, vcc
	v_lshlrev_b32_e32 v128, 16, v84
	v_and_b32_e32 v129, 0xffff0000, v84
	v_lshlrev_b32_e32 v130, 16, v85
	v_and_b32_e32 v131, 0xffff0000, v85
	v_lshlrev_b32_e32 v132, 16, v86
	v_and_b32_e32 v133, 0xffff0000, v86
	v_lshlrev_b32_e32 v134, 16, v87
	v_and_b32_e32 v135, 0xffff0000, v87
	v_pk_mul_f32 v[128:129], v[4:5], v[128:129] op_sel_hi:[0,1]
	v_pk_mul_f32 v[130:131], v[4:5], v[130:131] op_sel_hi:[0,1]
	v_pk_mul_f32 v[132:133], v[4:5], v[132:133] op_sel_hi:[0,1]
	v_pk_mul_f32 v[134:135], v[4:5], v[134:135] op_sel_hi:[0,1]
	v_pk_mul_f32 v[128:129], v[12:13], v[128:129]
	v_pk_mul_f32 v[130:131], v[14:15], v[130:131]
	v_pk_mul_f32 v[132:133], v[16:17], v[132:133]
	v_pk_mul_f32 v[134:135], v[18:19], v[134:135]
	s_and_saveexec_b64 s[28:29], s[20:21]
	global_store_dwordx4 v[90:91], v[104:107], off nt
	global_store_dwordx4 v[90:91], v[108:111], off offset:16 nt
	s_mov_b64 exec, s[28:29]
	s_and_saveexec_b64 s[28:29], s[22:23]
	global_store_dwordx4 v[92:93], v[112:115], off nt
	global_store_dwordx4 v[92:93], v[116:119], off offset:16 nt
	s_mov_b64 exec, s[28:29]
	s_and_saveexec_b64 s[28:29], s[24:25]
	global_store_dwordx4 v[94:95], v[120:123], off nt
	global_store_dwordx4 v[94:95], v[124:127], off offset:16 nt
	s_mov_b64 exec, s[28:29]
	s_and_saveexec_b64 s[28:29], s[26:27]
	global_store_dwordx4 v[96:97], v[128:131], off nt
	global_store_dwordx4 v[96:97], v[132:135], off offset:16 nt
	s_mov_b64 exec, s[28:29]
	s_andn2_b64 exec, exec, s[12:13]
	s_cbranch_execnz .Lfin_loop
